# in-proj slack late start + deferred accumulator zeroing + early A-slab DMA with vmcnt(24) at tile boundary
# speedup vs baseline: 1.0018x; 1.0018x over previous
; #define PG8_STAGE(bufoff, gbase, voff) do { _Pragma("unroll") for (int _i = 0; _i < 2; ++_i) \
;         __builtin_amdgcn_global_load_lds((const unsigned*)((const char*)(gbase) + (voff)[_i]), (LAS unsigned*)(lds + (bufoff) + ldsw + _i * 8192), 16, 0, 0); } while (0)
; #define PG8_LDA(dst, b, h) do { _Pragma("unroll") for (int m = 0; m < 4; ++m) _Pragma("unroll") for (int k = 0; k < 2; ++k) dst[m][k] = *(const LAS bf16x8*)(lds + PG8_SA(b, h) + aoff + m * 2048 + k * 1024); } while (0)
; #define PG8_LDB(dst, b, h) do { _Pragma("unroll") for (int n = 0; n < 2; ++n) _Pragma("unroll") for (int k = 0; k < 2; ++k) dst[n][k] = *(const LAS bf16x8*)(lds + PG8_SB(b, h) + boff + n * 2048 + k * 1024); } while (0)
; #define PG8_MMA(ai, bj, At, Bt) do { __builtin_amdgcn_s_setprio(1); _Pragma("unroll") for (int m = 0; m < 4; ++m) _Pragma("unroll") for (int n = 0; n < 2; ++n) _Pragma("unroll") for (int k = 0; k < 2; ++k) \
;         acc[ai][bj][m][n] = __builtin_amdgcn_mfma_f32_16x16x32_bf16(Bt[n][k], At[m][k], acc[ai][bj][m][n], 0, 0, 0); __builtin_amdgcn_s_setprio(0); } while (0)
; #define PG8_WAIT_V(n) asm volatile("s_waitcnt vmcnt(" #n ")" ::: "memory")
; #define PG8_WAIT_L(n) asm volatile("s_waitcnt lgkmcnt(" #n ")" ::: "memory")
; #define PG8_BAR __builtin_amdgcn_s_barrier()
; #define PG8_SCHED __builtin_amdgcn_sched_barrier(0)
; template <class Epi, class Sched>
; __device__ __forceinline__ void gemm_phase(LAS unsigned char* lds, const Gemm g, const Sched& S, const Epi& E) {
;     ...
;             PG8_WAIT_L(8); PG8_BAR; PG8_WAIT_L(0); PG8_MMA(0, 0, At, B0); PG8_BAR; PG8_SCHED;
;             PG8_LDB(B1, 0, 1); PG8_STAGE(PG8_SB(0, 0), b2, voffB);
;             PG8_BAR; PG8_WAIT_L(0); PG8_MMA(0, 1, At, B1); PG8_BAR;
;             PG8_LDA(At, 0, 1); PG8_STAGE(PG8_SA(0, 0), a2, voffA);
;             PG8_BAR; PG8_WAIT_L(0); PG8_MMA(1, 0, At, B0); PG8_BAR; PG8_SCHED;
;             PG8_STAGE(PG8_SB(0, 1), b2 + hstep, voffB);
;             PG8_WAIT_V(6); PG8_BAR; PG8_MMA(1, 1, At, B1); PG8_BAR;
.Lzd184:
	s_waitcnt lgkmcnt(8)
	s_barrier
	s_waitcnt lgkmcnt(0)
	s_setprio 1
	s_waitcnt lgkmcnt(0)
	v_mfma_f32_16x16x32_bf16 v[126:129], v[156:159], v[172:175], v[126:129]
	v_mfma_f32_16x16x32_bf16 v[122:125], v[164:167], v[172:175], v[122:125]
	v_mfma_f32_16x16x32_bf16 v[118:121], v[156:159], v[192:195], v[118:121]
	v_mfma_f32_16x16x32_bf16 v[110:113], v[164:167], v[192:195], v[110:113]
	v_mfma_f32_16x16x32_bf16 v[102:105], v[156:159], v[200:203], v[102:105]
	v_mfma_f32_16x16x32_bf16 v[94:97], v[164:167], v[200:203], v[94:97]
	v_mfma_f32_16x16x32_bf16 v[86:89], v[156:159], v[208:211], v[86:89]
	v_mfma_f32_16x16x32_bf16 v[78:81], v[164:167], v[208:211], v[78:81]
	v_mfma_f32_16x16x32_bf16 v[126:129], v[160:163], v[188:191], v[126:129]
	v_mfma_f32_16x16x32_bf16 v[122:125], v[168:171], v[188:191], v[122:125]
	v_mfma_f32_16x16x32_bf16 v[118:121], v[160:163], v[196:199], v[118:121]
	v_mfma_f32_16x16x32_bf16 v[110:113], v[168:171], v[196:199], v[110:113]
	v_mfma_f32_16x16x32_bf16 v[102:105], v[160:163], v[204:207], v[102:105]
	v_mfma_f32_16x16x32_bf16 v[94:97], v[168:171], v[204:207], v[94:97]
	v_mfma_f32_16x16x32_bf16 v[86:89], v[160:163], v[212:215], v[86:89]
	v_mfma_f32_16x16x32_bf16 v[78:81], v[168:171], v[212:215], v[78:81]
	s_setprio 0
	s_barrier
	s_add_i32 s23, 16, 0x14000
	s_add_i32 s20, s22, s8
	v_add_u32_e32 v153, s23, v154
	v_lshl_add_u64 v[232:233], s[66:67], 0, v[144:145]
	s_mov_b32 m0, s20
	ds_read_b128 v[216:219], v153
	ds_read_b128 v[220:223], v153 offset:1024
	ds_read_b128 v[224:227], v153 offset:2048
	ds_read_b128 v[228:231], v153 offset:3072
	global_load_lds_dwordx4 v[232:233], off
	v_lshl_add_u64 v[234:235], s[66:67], 0, v[140:141]
	s_add_i32 m0, s20, 0x2000
	s_nop 0
	global_load_lds_dwordx4 v[234:235], off
	s_barrier
	s_waitcnt lgkmcnt(0)
	s_setprio 1
	s_waitcnt lgkmcnt(0)
	v_mfma_f32_16x16x32_bf16 v[114:117], v[216:219], v[172:175], v[114:117]
	v_mfma_f32_16x16x32_bf16 v[106:109], v[224:227], v[172:175], v[106:109]
	v_mfma_f32_16x16x32_bf16 v[98:101], v[216:219], v[192:195], v[98:101]
	v_mfma_f32_16x16x32_bf16 v[90:93], v[224:227], v[192:195], v[90:93]
	v_mfma_f32_16x16x32_bf16 v[82:85], v[216:219], v[200:203], v[82:85]
	v_mfma_f32_16x16x32_bf16 v[74:77], v[224:227], v[200:203], v[74:77]
	v_mfma_f32_16x16x32_bf16 v[70:73], v[216:219], v[208:211], v[70:73]
	v_mfma_f32_16x16x32_bf16 v[66:69], v[224:227], v[208:211], v[66:69]
	v_mfma_f32_16x16x32_bf16 v[114:117], v[220:223], v[188:191], v[114:117]
	v_mfma_f32_16x16x32_bf16 v[106:109], v[228:231], v[188:191], v[106:109]
	v_mfma_f32_16x16x32_bf16 v[98:101], v[220:223], v[196:199], v[98:101]
	v_mfma_f32_16x16x32_bf16 v[90:93], v[228:231], v[196:199], v[90:93]
	v_mfma_f32_16x16x32_bf16 v[82:85], v[220:223], v[204:207], v[82:85]
	v_mfma_f32_16x16x32_bf16 v[74:77], v[228:231], v[204:207], v[74:77]
	v_mfma_f32_16x16x32_bf16 v[70:73], v[220:223], v[212:215], v[70:73]
	v_mfma_f32_16x16x32_bf16 v[66:69], v[228:231], v[212:215], v[66:69]
	s_setprio 0
	s_mov_b32 m0, s9
	v_lshl_add_u64 v[236:237], s[70:71], 0, v[146:147]
	s_barrier
	ds_read_b128 v[172:175], v155 offset:16384
	ds_read_b128 v[188:191], v155 offset:17408
	ds_read_b128 v[192:195], v155 offset:18432
	ds_read_b128 v[196:199], v155 offset:19456
	ds_read_b128 v[200:203], v155 offset:20480
	ds_read_b128 v[204:207], v155 offset:21504
	ds_read_b128 v[208:211], v155 offset:22528
	ds_read_b128 v[212:215], v155 offset:23552
	global_load_lds_dwordx4 v[236:237], off
	v_lshl_add_u64 v[238:239], s[70:71], 0, v[142:143]
	s_mov_b32 m0, s10
	s_nop 0
	global_load_lds_dwordx4 v[238:239], off
	s_barrier
	s_waitcnt lgkmcnt(0)
	s_setprio 1
	s_waitcnt lgkmcnt(0)
	v_mfma_f32_16x16x32_bf16 v[62:65], v[156:159], v[172:175], v[62:65]
	v_mfma_f32_16x16x32_bf16 v[58:61], v[164:167], v[172:175], v[58:61]
	v_mfma_f32_16x16x32_bf16 v[54:57], v[156:159], v[192:195], v[54:57]
	v_mfma_f32_16x16x32_bf16 v[50:53], v[164:167], v[192:195], v[50:53]
	v_mfma_f32_16x16x32_bf16 v[38:41], v[156:159], v[200:203], v[38:41]
	v_mfma_f32_16x16x32_bf16 v[34:37], v[164:167], v[200:203], v[34:37]
	v_mfma_f32_16x16x32_bf16 v[22:25], v[156:159], v[208:211], v[22:25]
	v_mfma_f32_16x16x32_bf16 v[18:21], v[164:167], v[208:211], v[18:21]
	v_mfma_f32_16x16x32_bf16 v[62:65], v[160:163], v[188:191], v[62:65]
	v_mfma_f32_16x16x32_bf16 v[58:61], v[168:171], v[188:191], v[58:61]
	v_mfma_f32_16x16x32_bf16 v[54:57], v[160:163], v[196:199], v[54:57]
	v_mfma_f32_16x16x32_bf16 v[50:53], v[168:171], v[196:199], v[50:53]
	v_mfma_f32_16x16x32_bf16 v[38:41], v[160:163], v[204:207], v[38:41]
	v_mfma_f32_16x16x32_bf16 v[34:37], v[168:171], v[204:207], v[34:37]
	v_mfma_f32_16x16x32_bf16 v[22:25], v[160:163], v[212:215], v[22:25]
	v_mfma_f32_16x16x32_bf16 v[18:21], v[168:171], v[212:215], v[18:21]
	s_setprio 0
	s_barrier
	s_add_u32 s20, s66, 0x40000
	s_addc_u32 s21, s67, 0
	s_add_i32 s22, s23, s8
	v_lshl_add_u64 v[156:157], s[20:21], 0, v[144:145]
	s_mov_b32 m0, s22
	s_nop 0
	global_load_lds_dwordx4 v[156:157], off
	v_lshl_add_u64 v[156:157], s[20:21], 0, v[140:141]
	s_add_i32 m0, s22, 0x2000
	s_nop 0
	global_load_lds_dwordx4 v[156:157], off
	s_cmp_eq_u32 s98, 0
	s_cbranch_scc1 .Lgdr184_n
	s_waitcnt vmcnt(24)
	s_mov_b32 s98, 0
	s_branch .Lgdr184_j

; #define PG8_STAGE(bufoff, gbase, voff) do { _Pragma("unroll") for (int _i = 0; _i < 2; ++_i) \
;         __builtin_amdgcn_global_load_lds((const unsigned*)((const char*)(gbase) + (voff)[_i]), (LAS unsigned*)(lds + (bufoff) + ldsw + _i * 8192), 16, 0, 0); } while (0)
; #define PG8_LDA(dst, b, h) do { _Pragma("unroll") for (int m = 0; m < 4; ++m) _Pragma("unroll") for (int k = 0; k < 2; ++k) dst[m][k] = *(const LAS bf16x8*)(lds + PG8_SA(b, h) + aoff + m * 2048 + k * 1024); } while (0)
; #define PG8_LDB(dst, b, h) do { _Pragma("unroll") for (int n = 0; n < 2; ++n) _Pragma("unroll") for (int k = 0; k < 2; ++k) dst[n][k] = *(const LAS bf16x8*)(lds + PG8_SB(b, h) + boff + n * 2048 + k * 1024); } while (0)
; #define PG8_MMA(ai, bj, At, Bt) do { __builtin_amdgcn_s_setprio(1); _Pragma("unroll") for (int m = 0; m < 4; ++m) _Pragma("unroll") for (int n = 0; n < 2; ++n) _Pragma("unroll") for (int k = 0; k < 2; ++k) \
;         acc[ai][bj][m][n] = __builtin_amdgcn_mfma_f32_16x16x32_bf16(Bt[n][k], At[m][k], acc[ai][bj][m][n], 0, 0, 0); __builtin_amdgcn_s_setprio(0); } while (0)
; #define PG8_WAIT_V(n) asm volatile("s_waitcnt vmcnt(" #n ")" ::: "memory")
; #define PG8_WAIT_L(n) asm volatile("s_waitcnt lgkmcnt(" #n ")" ::: "memory")
; #define PG8_BAR __builtin_amdgcn_s_barrier()
; #define PG8_SCHED __builtin_amdgcn_sched_barrier(0)
; template <class Epi, class Sched>
; __device__ __forceinline__ void gemm_phase(LAS unsigned char* lds, const Gemm g, const Sched& S, const Epi& E) {
;     ...
;             PG8_WAIT_L(8); PG8_BAR; PG8_WAIT_L(0); PG8_MMA(0, 0, At, B0); PG8_BAR; PG8_SCHED;
;             PG8_LDB(B1, 0, 1); PG8_STAGE(PG8_SB(0, 0), b2, voffB);
;             PG8_BAR; PG8_WAIT_L(0); PG8_MMA(0, 1, At, B1); PG8_BAR;
;             PG8_LDA(At, 0, 1); PG8_STAGE(PG8_SA(0, 0), a2, voffA);
;             PG8_BAR; PG8_WAIT_L(0); PG8_MMA(1, 0, At, B0); PG8_BAR; PG8_SCHED;
;             PG8_STAGE(PG8_SB(0, 1), b2 + hstep, voffB);
;             PG8_WAIT_V(6); PG8_BAR; PG8_MMA(1, 1, At, B1); PG8_BAR;
.Lzd512:
	s_waitcnt lgkmcnt(8)
	s_barrier
	s_waitcnt lgkmcnt(0)
	s_setprio 1
	s_waitcnt lgkmcnt(0)
	v_mfma_f32_16x16x32_bf16 v[126:129], v[156:159], v[172:175], v[126:129]
	v_mfma_f32_16x16x32_bf16 v[122:125], v[164:167], v[172:175], v[122:125]
	v_mfma_f32_16x16x32_bf16 v[118:121], v[156:159], v[192:195], v[118:121]
	v_mfma_f32_16x16x32_bf16 v[114:117], v[164:167], v[192:195], v[114:117]
	v_mfma_f32_16x16x32_bf16 v[102:105], v[156:159], v[200:203], v[102:105]
	v_mfma_f32_16x16x32_bf16 v[98:101], v[164:167], v[200:203], v[98:101]
	v_mfma_f32_16x16x32_bf16 v[86:89], v[156:159], v[208:211], v[86:89]
	v_mfma_f32_16x16x32_bf16 v[82:85], v[164:167], v[208:211], v[82:85]
	v_mfma_f32_16x16x32_bf16 v[126:129], v[160:163], v[188:191], v[126:129]
	v_mfma_f32_16x16x32_bf16 v[122:125], v[168:171], v[188:191], v[122:125]
	v_mfma_f32_16x16x32_bf16 v[118:121], v[160:163], v[196:199], v[118:121]
	v_mfma_f32_16x16x32_bf16 v[114:117], v[168:171], v[196:199], v[114:117]
	v_mfma_f32_16x16x32_bf16 v[102:105], v[160:163], v[204:207], v[102:105]
	v_mfma_f32_16x16x32_bf16 v[98:101], v[168:171], v[204:207], v[98:101]
	v_mfma_f32_16x16x32_bf16 v[86:89], v[160:163], v[212:215], v[86:89]
	v_mfma_f32_16x16x32_bf16 v[82:85], v[168:171], v[212:215], v[82:85]
	s_setprio 0
	s_barrier
	s_add_i32 s23, 16, 0x14000
	s_add_i32 s20, s22, s9
	v_add_u32_e32 v155, s23, v152
	v_lshl_add_u64 v[232:233], s[66:67], 0, v[144:145]
	s_mov_b32 m0, s20
	ds_read_b128 v[216:219], v155
	ds_read_b128 v[220:223], v155 offset:1024
	ds_read_b128 v[224:227], v155 offset:2048
	ds_read_b128 v[228:231], v155 offset:3072
	global_load_lds_dwordx4 v[232:233], off
	v_lshl_add_u64 v[234:235], s[66:67], 0, v[140:141]
	s_add_i32 m0, s20, 0x2000
	s_nop 0
	global_load_lds_dwordx4 v[234:235], off
	s_barrier
	s_waitcnt lgkmcnt(0)
	s_setprio 1
	s_waitcnt lgkmcnt(0)
	v_mfma_f32_16x16x32_bf16 v[110:113], v[216:219], v[172:175], v[110:113]
	v_mfma_f32_16x16x32_bf16 v[106:109], v[224:227], v[172:175], v[106:109]
	v_mfma_f32_16x16x32_bf16 v[94:97], v[216:219], v[192:195], v[94:97]
	v_mfma_f32_16x16x32_bf16 v[90:93], v[224:227], v[192:195], v[90:93]
	v_mfma_f32_16x16x32_bf16 v[78:81], v[216:219], v[200:203], v[78:81]
	v_mfma_f32_16x16x32_bf16 v[74:77], v[224:227], v[200:203], v[74:77]
	v_mfma_f32_16x16x32_bf16 v[70:73], v[216:219], v[208:211], v[70:73]
	v_mfma_f32_16x16x32_bf16 v[66:69], v[224:227], v[208:211], v[66:69]
	v_mfma_f32_16x16x32_bf16 v[110:113], v[220:223], v[188:191], v[110:113]
	v_mfma_f32_16x16x32_bf16 v[106:109], v[228:231], v[188:191], v[106:109]
	v_mfma_f32_16x16x32_bf16 v[94:97], v[220:223], v[196:199], v[94:97]
	v_mfma_f32_16x16x32_bf16 v[90:93], v[228:231], v[196:199], v[90:93]
	v_mfma_f32_16x16x32_bf16 v[78:81], v[220:223], v[204:207], v[78:81]
	v_mfma_f32_16x16x32_bf16 v[74:77], v[228:231], v[204:207], v[74:77]
	v_mfma_f32_16x16x32_bf16 v[70:73], v[220:223], v[212:215], v[70:73]
	v_mfma_f32_16x16x32_bf16 v[66:69], v[228:231], v[212:215], v[66:69]
	s_setprio 0
	s_mov_b32 m0, s1
	v_lshl_add_u64 v[236:237], s[72:73], 0, v[146:147]
	s_barrier
	ds_read_b128 v[172:175], v154 offset:16384
	ds_read_b128 v[188:191], v154 offset:17408
	ds_read_b128 v[192:195], v154 offset:18432
	ds_read_b128 v[196:199], v154 offset:19456
	ds_read_b128 v[200:203], v154 offset:20480
	ds_read_b128 v[204:207], v154 offset:21504
	ds_read_b128 v[208:211], v154 offset:22528
	ds_read_b128 v[212:215], v154 offset:23552
	global_load_lds_dwordx4 v[236:237], off
	v_lshl_add_u64 v[238:239], s[72:73], 0, v[142:143]
	s_mov_b32 m0, s11
	s_nop 0
	global_load_lds_dwordx4 v[238:239], off
	s_barrier
	s_waitcnt lgkmcnt(0)
	s_setprio 1
	s_waitcnt lgkmcnt(0)
	v_mfma_f32_16x16x32_bf16 v[62:65], v[156:159], v[172:175], v[62:65]
	v_mfma_f32_16x16x32_bf16 v[58:61], v[164:167], v[172:175], v[58:61]
	v_mfma_f32_16x16x32_bf16 v[54:57], v[156:159], v[192:195], v[54:57]
	v_mfma_f32_16x16x32_bf16 v[50:53], v[164:167], v[192:195], v[50:53]
	v_mfma_f32_16x16x32_bf16 v[38:41], v[156:159], v[200:203], v[38:41]
	v_mfma_f32_16x16x32_bf16 v[34:37], v[164:167], v[200:203], v[34:37]
	v_mfma_f32_16x16x32_bf16 v[22:25], v[156:159], v[208:211], v[22:25]
	v_mfma_f32_16x16x32_bf16 v[18:21], v[164:167], v[208:211], v[18:21]
	v_mfma_f32_16x16x32_bf16 v[62:65], v[160:163], v[188:191], v[62:65]
	v_mfma_f32_16x16x32_bf16 v[58:61], v[168:171], v[188:191], v[58:61]
	v_mfma_f32_16x16x32_bf16 v[54:57], v[160:163], v[196:199], v[54:57]
	v_mfma_f32_16x16x32_bf16 v[50:53], v[168:171], v[196:199], v[50:53]
	v_mfma_f32_16x16x32_bf16 v[38:41], v[160:163], v[204:207], v[38:41]
	v_mfma_f32_16x16x32_bf16 v[34:37], v[168:171], v[204:207], v[34:37]
	v_mfma_f32_16x16x32_bf16 v[22:25], v[160:163], v[212:215], v[22:25]
	v_mfma_f32_16x16x32_bf16 v[18:21], v[168:171], v[212:215], v[18:21]
	s_setprio 0
	s_barrier
	s_add_u32 s20, s66, 0x40000
	s_addc_u32 s21, s67, 0
	s_add_i32 s22, s23, s9
	v_lshl_add_u64 v[156:157], s[20:21], 0, v[144:145]
	s_mov_b32 m0, s22
	s_nop 0
	global_load_lds_dwordx4 v[156:157], off
	v_lshl_add_u64 v[156:157], s[20:21], 0, v[140:141]
	s_add_i32 m0, s22, 0x2000
	s_nop 0
	global_load_lds_dwordx4 v[156:157], off
	s_cmp_eq_u32 s98, 0
	s_cbranch_scc1 .Lgdr512_n
	s_waitcnt vmcnt(24)
	s_mov_b32 s98, 0
	s_branch .Lgdr512_j

; #define PG8_STAGE(bufoff, gbase, voff) do { _Pragma("unroll") for (int _i = 0; _i < 2; ++_i) \
;         __builtin_amdgcn_global_load_lds((const unsigned*)((const char*)(gbase) + (voff)[_i]), (LAS unsigned*)(lds + (bufoff) + ldsw + _i * 8192), 16, 0, 0); } while (0)
; #define PG8_LDA(dst, b, h) do { _Pragma("unroll") for (int m = 0; m < 4; ++m) _Pragma("unroll") for (int k = 0; k < 2; ++k) dst[m][k] = *(const LAS bf16x8*)(lds + PG8_SA(b, h) + aoff + m * 2048 + k * 1024); } while (0)
; #define PG8_LDB(dst, b, h) do { _Pragma("unroll") for (int n = 0; n < 2; ++n) _Pragma("unroll") for (int k = 0; k < 2; ++k) dst[n][k] = *(const LAS bf16x8*)(lds + PG8_SB(b, h) + boff + n * 2048 + k * 1024); } while (0)
; #define PG8_MMA(ai, bj, At, Bt) do { __builtin_amdgcn_s_setprio(1); _Pragma("unroll") for (int m = 0; m < 4; ++m) _Pragma("unroll") for (int n = 0; n < 2; ++n) _Pragma("unroll") for (int k = 0; k < 2; ++k) \
;         acc[ai][bj][m][n] = __builtin_amdgcn_mfma_f32_16x16x32_bf16(Bt[n][k], At[m][k], acc[ai][bj][m][n], 0, 0, 0); __builtin_amdgcn_s_setprio(0); } while (0)
; #define PG8_WAIT_V(n) asm volatile("s_waitcnt vmcnt(" #n ")" ::: "memory")
; #define PG8_WAIT_L(n) asm volatile("s_waitcnt lgkmcnt(" #n ")" ::: "memory")
; #define PG8_BAR __builtin_amdgcn_s_barrier()
; #define PG8_SCHED __builtin_amdgcn_sched_barrier(0)
; template <class Epi, class Sched>
; __device__ __forceinline__ void gemm_phase(LAS unsigned char* lds, const Gemm g, const Sched& S, const Epi& E) {
;     ...
;             PG8_WAIT_L(8); PG8_BAR; PG8_WAIT_L(0); PG8_MMA(0, 0, At, B0); PG8_BAR; PG8_SCHED;
;             PG8_LDB(B1, 0, 1); PG8_STAGE(PG8_SB(0, 0), b2, voffB);
;             PG8_BAR; PG8_WAIT_L(0); PG8_MMA(0, 1, At, B1); PG8_BAR;
;             PG8_LDA(At, 0, 1); PG8_STAGE(PG8_SA(0, 0), a2, voffA);
;             PG8_BAR; PG8_WAIT_L(0); PG8_MMA(1, 0, At, B0); PG8_BAR; PG8_SCHED;
;             PG8_STAGE(PG8_SB(0, 1), b2 + hstep, voffB);
;             PG8_WAIT_V(6); PG8_BAR; PG8_MMA(1, 1, At, B1); PG8_BAR;
.Lzd643:
	s_waitcnt lgkmcnt(8)
	s_barrier
	s_waitcnt lgkmcnt(0)
	s_setprio 1
	s_waitcnt lgkmcnt(0)
	v_mfma_f32_16x16x32_bf16 v[126:129], v[156:159], v[172:175], v[126:129]
	v_mfma_f32_16x16x32_bf16 v[122:125], v[164:167], v[172:175], v[122:125]
	v_mfma_f32_16x16x32_bf16 v[118:121], v[156:159], v[192:195], v[118:121]
	v_mfma_f32_16x16x32_bf16 v[114:117], v[164:167], v[192:195], v[114:117]
	v_mfma_f32_16x16x32_bf16 v[102:105], v[156:159], v[200:203], v[102:105]
	v_mfma_f32_16x16x32_bf16 v[98:101], v[164:167], v[200:203], v[98:101]
	v_mfma_f32_16x16x32_bf16 v[86:89], v[156:159], v[208:211], v[86:89]
	v_mfma_f32_16x16x32_bf16 v[82:85], v[164:167], v[208:211], v[82:85]
	v_mfma_f32_16x16x32_bf16 v[126:129], v[160:163], v[188:191], v[126:129]
	v_mfma_f32_16x16x32_bf16 v[122:125], v[168:171], v[188:191], v[122:125]
	v_mfma_f32_16x16x32_bf16 v[118:121], v[160:163], v[196:199], v[118:121]
	v_mfma_f32_16x16x32_bf16 v[114:117], v[168:171], v[196:199], v[114:117]
	v_mfma_f32_16x16x32_bf16 v[102:105], v[160:163], v[204:207], v[102:105]
	v_mfma_f32_16x16x32_bf16 v[98:101], v[168:171], v[204:207], v[98:101]
	v_mfma_f32_16x16x32_bf16 v[86:89], v[160:163], v[212:215], v[86:89]
	v_mfma_f32_16x16x32_bf16 v[82:85], v[168:171], v[212:215], v[82:85]
	s_setprio 0
	s_barrier
	s_add_i32 s21, 16, 0x14000
	s_add_i32 s22, s23, s9
	v_add_u32_e32 v155, s21, v152
	v_lshl_add_u64 v[232:233], s[70:71], 0, v[144:145]
	s_mov_b32 m0, s22
	ds_read_b128 v[216:219], v155
	ds_read_b128 v[220:223], v155 offset:1024
	ds_read_b128 v[224:227], v155 offset:2048
	ds_read_b128 v[228:231], v155 offset:3072
	global_load_lds_dwordx4 v[232:233], off
	v_lshl_add_u64 v[234:235], s[70:71], 0, v[140:141]
	s_add_i32 m0, s22, 0x2000
	s_nop 0
	global_load_lds_dwordx4 v[234:235], off
	s_barrier
	s_waitcnt lgkmcnt(0)
	s_setprio 1
	s_waitcnt lgkmcnt(0)
	v_mfma_f32_16x16x32_bf16 v[110:113], v[216:219], v[172:175], v[110:113]
	v_mfma_f32_16x16x32_bf16 v[106:109], v[224:227], v[172:175], v[106:109]
	v_mfma_f32_16x16x32_bf16 v[94:97], v[216:219], v[192:195], v[94:97]
	v_mfma_f32_16x16x32_bf16 v[90:93], v[224:227], v[192:195], v[90:93]
	v_mfma_f32_16x16x32_bf16 v[78:81], v[216:219], v[200:203], v[78:81]
	v_mfma_f32_16x16x32_bf16 v[74:77], v[224:227], v[200:203], v[74:77]
	v_mfma_f32_16x16x32_bf16 v[70:73], v[216:219], v[208:211], v[70:73]
	v_mfma_f32_16x16x32_bf16 v[66:69], v[224:227], v[208:211], v[66:69]
	v_mfma_f32_16x16x32_bf16 v[110:113], v[220:223], v[188:191], v[110:113]
	v_mfma_f32_16x16x32_bf16 v[106:109], v[228:231], v[188:191], v[106:109]
	v_mfma_f32_16x16x32_bf16 v[94:97], v[220:223], v[196:199], v[94:97]
	v_mfma_f32_16x16x32_bf16 v[90:93], v[228:231], v[196:199], v[90:93]
	v_mfma_f32_16x16x32_bf16 v[78:81], v[220:223], v[204:207], v[78:81]
	v_mfma_f32_16x16x32_bf16 v[74:77], v[228:231], v[204:207], v[74:77]
	v_mfma_f32_16x16x32_bf16 v[70:73], v[220:223], v[212:215], v[70:73]
	v_mfma_f32_16x16x32_bf16 v[66:69], v[228:231], v[212:215], v[66:69]
	s_setprio 0
	s_mov_b32 m0, s11
	v_lshl_add_u64 v[236:237], s[78:79], 0, v[146:147]
	s_barrier
	ds_read_b128 v[172:175], v154 offset:16384
	ds_read_b128 v[188:191], v154 offset:17408
	ds_read_b128 v[192:195], v154 offset:18432
	ds_read_b128 v[196:199], v154 offset:19456
	ds_read_b128 v[200:203], v154 offset:20480
	ds_read_b128 v[204:207], v154 offset:21504
	ds_read_b128 v[208:211], v154 offset:22528
	ds_read_b128 v[212:215], v154 offset:23552
	global_load_lds_dwordx4 v[236:237], off
	v_lshl_add_u64 v[238:239], s[78:79], 0, v[142:143]
	s_mov_b32 m0, s41
	s_nop 0
	global_load_lds_dwordx4 v[238:239], off
	s_barrier
	s_waitcnt lgkmcnt(0)
	s_setprio 1
	s_waitcnt lgkmcnt(0)
	v_mfma_f32_16x16x32_bf16 v[62:65], v[156:159], v[172:175], v[62:65]
	v_mfma_f32_16x16x32_bf16 v[58:61], v[164:167], v[172:175], v[58:61]
	v_mfma_f32_16x16x32_bf16 v[54:57], v[156:159], v[192:195], v[54:57]
	v_mfma_f32_16x16x32_bf16 v[50:53], v[164:167], v[192:195], v[50:53]
	v_mfma_f32_16x16x32_bf16 v[38:41], v[156:159], v[200:203], v[38:41]
	v_mfma_f32_16x16x32_bf16 v[34:37], v[164:167], v[200:203], v[34:37]
	v_mfma_f32_16x16x32_bf16 v[22:25], v[156:159], v[208:211], v[22:25]
	v_mfma_f32_16x16x32_bf16 v[18:21], v[164:167], v[208:211], v[18:21]
	v_mfma_f32_16x16x32_bf16 v[62:65], v[160:163], v[188:191], v[62:65]
	v_mfma_f32_16x16x32_bf16 v[58:61], v[168:171], v[188:191], v[58:61]
	v_mfma_f32_16x16x32_bf16 v[54:57], v[160:163], v[196:199], v[54:57]
	v_mfma_f32_16x16x32_bf16 v[50:53], v[168:171], v[196:199], v[50:53]
	v_mfma_f32_16x16x32_bf16 v[38:41], v[160:163], v[204:207], v[38:41]
	v_mfma_f32_16x16x32_bf16 v[34:37], v[168:171], v[204:207], v[34:37]
	v_mfma_f32_16x16x32_bf16 v[22:25], v[160:163], v[212:215], v[22:25]
	v_mfma_f32_16x16x32_bf16 v[18:21], v[168:171], v[212:215], v[18:21]
	s_setprio 0
	s_barrier
	s_add_u32 s22, s70, 0x40000
	s_addc_u32 s23, s71, 0
	s_add_i32 s21, s21, s9
	v_lshl_add_u64 v[156:157], s[22:23], 0, v[144:145]
	s_mov_b32 m0, s21
	s_nop 0
	global_load_lds_dwordx4 v[156:157], off
	v_lshl_add_u64 v[156:157], s[22:23], 0, v[140:141]
	s_add_i32 m0, s21, 0x2000
	s_nop 0
	global_load_lds_dwordx4 v[156:157], off
	s_cmp_eq_u32 s98, 0
	s_cbranch_scc1 .Lgdr643_n
	s_waitcnt vmcnt(24)
	s_mov_b32 s98, 0
	s_branch .Lgdr643_j

; #define PG8_STAGE(bufoff, gbase, voff) do { _Pragma("unroll") for (int _i = 0; _i < 2; ++_i) \
;         __builtin_amdgcn_global_load_lds((const unsigned*)((const char*)(gbase) + (voff)[_i]), (LAS unsigned*)(lds + (bufoff) + ldsw + _i * 8192), 16, 0, 0); } while (0)
; #define PG8_LDA(dst, b, h) do { _Pragma("unroll") for (int m = 0; m < 4; ++m) _Pragma("unroll") for (int k = 0; k < 2; ++k) dst[m][k] = *(const LAS bf16x8*)(lds + PG8_SA(b, h) + aoff + m * 2048 + k * 1024); } while (0)
; #define PG8_LDB(dst, b, h) do { _Pragma("unroll") for (int n = 0; n < 2; ++n) _Pragma("unroll") for (int k = 0; k < 2; ++k) dst[n][k] = *(const LAS bf16x8*)(lds + PG8_SB(b, h) + boff + n * 2048 + k * 1024); } while (0)
; #define PG8_MMA(ai, bj, At, Bt) do { __builtin_amdgcn_s_setprio(1); _Pragma("unroll") for (int m = 0; m < 4; ++m) _Pragma("unroll") for (int n = 0; n < 2; ++n) _Pragma("unroll") for (int k = 0; k < 2; ++k) \
;         acc[ai][bj][m][n] = __builtin_amdgcn_mfma_f32_16x16x32_bf16(Bt[n][k], At[m][k], acc[ai][bj][m][n], 0, 0, 0); __builtin_amdgcn_s_setprio(0); } while (0)
; #define PG8_WAIT_V(n) asm volatile("s_waitcnt vmcnt(" #n ")" ::: "memory")
; #define PG8_WAIT_L(n) asm volatile("s_waitcnt lgkmcnt(" #n ")" ::: "memory")
; #define PG8_BAR __builtin_amdgcn_s_barrier()
; #define PG8_SCHED __builtin_amdgcn_sched_barrier(0)
; template <class Epi, class Sched>
; __device__ __forceinline__ void gemm_phase(LAS unsigned char* lds, const Gemm g, const Sched& S, const Epi& E) {
;     ...
;             PG8_LDB(B0, 0, 0); PG8_SCHED; PG8_LDA(At, 0, 0); PG8_STAGE(PG8_SA(1, 1), a1 + hstep, voffA);
;             PG8_WAIT_L(8); PG8_BAR; PG8_WAIT_L(0); PG8_MMA(0, 0, At, B0); PG8_BAR; PG8_SCHED;
;             PG8_LDB(B1, 0, 1); PG8_STAGE(PG8_SB(0, 0), b2, voffB);
;             PG8_BAR; PG8_WAIT_L(0); PG8_MMA(0, 1, At, B1); PG8_BAR;
;             PG8_LDA(At, 0, 1); PG8_STAGE(PG8_SA(0, 0), a2, voffA);
;             PG8_BAR; PG8_WAIT_L(0); PG8_MMA(1, 0, At, B0); PG8_BAR; PG8_SCHED;
;             PG8_STAGE(PG8_SB(0, 1), b2 + hstep, voffB);
;             PG8_WAIT_V(6); PG8_BAR; PG8_MMA(1, 1, At, B1); PG8_BAR;
.Lzd818:
	s_waitcnt lgkmcnt(8)
	s_barrier
	s_waitcnt lgkmcnt(0)
	s_setprio 1
	s_waitcnt lgkmcnt(0)
	v_mfma_f32_16x16x32_bf16 v[126:129], v[156:159], v[172:175], v[126:129]
	v_mfma_f32_16x16x32_bf16 v[122:125], v[164:167], v[172:175], v[122:125]
	v_mfma_f32_16x16x32_bf16 v[118:121], v[156:159], v[192:195], v[118:121]
	v_mfma_f32_16x16x32_bf16 v[114:117], v[164:167], v[192:195], v[114:117]
	v_mfma_f32_16x16x32_bf16 v[102:105], v[156:159], v[200:203], v[102:105]
	v_mfma_f32_16x16x32_bf16 v[98:101], v[164:167], v[200:203], v[98:101]
	v_mfma_f32_16x16x32_bf16 v[86:89], v[156:159], v[208:211], v[86:89]
	v_mfma_f32_16x16x32_bf16 v[82:85], v[164:167], v[208:211], v[82:85]
	v_mfma_f32_16x16x32_bf16 v[126:129], v[160:163], v[188:191], v[126:129]
	v_mfma_f32_16x16x32_bf16 v[122:125], v[168:171], v[188:191], v[122:125]
	v_mfma_f32_16x16x32_bf16 v[118:121], v[160:163], v[196:199], v[118:121]
	v_mfma_f32_16x16x32_bf16 v[114:117], v[168:171], v[196:199], v[114:117]
	v_mfma_f32_16x16x32_bf16 v[102:105], v[160:163], v[204:207], v[102:105]
	v_mfma_f32_16x16x32_bf16 v[98:101], v[168:171], v[204:207], v[98:101]
	v_mfma_f32_16x16x32_bf16 v[86:89], v[160:163], v[212:215], v[86:89]
	v_mfma_f32_16x16x32_bf16 v[82:85], v[168:171], v[212:215], v[82:85]
	s_setprio 0
	s_barrier
	s_add_i32 s22, 16, 0x14000
	s_add_i32 s19, s19, s9
	v_add_u32_e32 v155, s22, v152
	v_lshl_add_u64 v[232:233], s[66:67], 0, v[144:145]
	s_mov_b32 m0, s19
	ds_read_b128 v[216:219], v155
	ds_read_b128 v[220:223], v155 offset:1024
	ds_read_b128 v[224:227], v155 offset:2048
	ds_read_b128 v[228:231], v155 offset:3072
	global_load_lds_dwordx4 v[232:233], off
	v_lshl_add_u64 v[234:235], s[66:67], 0, v[140:141]
	s_add_i32 m0, s19, 0x2000
	s_nop 0
	global_load_lds_dwordx4 v[234:235], off
	s_barrier
	s_waitcnt lgkmcnt(0)
	s_setprio 1
	s_waitcnt lgkmcnt(0)
	v_mfma_f32_16x16x32_bf16 v[110:113], v[216:219], v[172:175], v[110:113]
	v_mfma_f32_16x16x32_bf16 v[106:109], v[224:227], v[172:175], v[106:109]
	v_mfma_f32_16x16x32_bf16 v[94:97], v[216:219], v[192:195], v[94:97]
	v_mfma_f32_16x16x32_bf16 v[90:93], v[224:227], v[192:195], v[90:93]
	v_mfma_f32_16x16x32_bf16 v[78:81], v[216:219], v[200:203], v[78:81]
	v_mfma_f32_16x16x32_bf16 v[74:77], v[224:227], v[200:203], v[74:77]
	v_mfma_f32_16x16x32_bf16 v[70:73], v[216:219], v[208:211], v[70:73]
	v_mfma_f32_16x16x32_bf16 v[66:69], v[224:227], v[208:211], v[66:69]
	v_mfma_f32_16x16x32_bf16 v[110:113], v[220:223], v[188:191], v[110:113]
	v_mfma_f32_16x16x32_bf16 v[106:109], v[228:231], v[188:191], v[106:109]
	v_mfma_f32_16x16x32_bf16 v[94:97], v[220:223], v[196:199], v[94:97]
	v_mfma_f32_16x16x32_bf16 v[90:93], v[228:231], v[196:199], v[90:93]
	v_mfma_f32_16x16x32_bf16 v[78:81], v[220:223], v[204:207], v[78:81]
	v_mfma_f32_16x16x32_bf16 v[74:77], v[228:231], v[204:207], v[74:77]
	v_mfma_f32_16x16x32_bf16 v[70:73], v[220:223], v[212:215], v[70:73]
	v_mfma_f32_16x16x32_bf16 v[66:69], v[228:231], v[212:215], v[66:69]
	s_setprio 0
	s_mov_b32 m0, s11
	v_lshl_add_u64 v[236:237], s[70:71], 0, v[146:147]
	s_barrier
	ds_read_b128 v[172:175], v154 offset:16384
	ds_read_b128 v[188:191], v154 offset:17408
	ds_read_b128 v[192:195], v154 offset:18432
	ds_read_b128 v[196:199], v154 offset:19456
	ds_read_b128 v[200:203], v154 offset:20480
	ds_read_b128 v[204:207], v154 offset:21504
	ds_read_b128 v[208:211], v154 offset:22528
	ds_read_b128 v[212:215], v154 offset:23552
	global_load_lds_dwordx4 v[236:237], off
	v_lshl_add_u64 v[238:239], s[70:71], 0, v[142:143]
	s_mov_b32 m0, s74
	s_nop 0
	global_load_lds_dwordx4 v[238:239], off
	s_barrier
	s_waitcnt lgkmcnt(0)
	s_setprio 1
	s_waitcnt lgkmcnt(0)
	v_mfma_f32_16x16x32_bf16 v[62:65], v[156:159], v[172:175], v[62:65]
	v_mfma_f32_16x16x32_bf16 v[58:61], v[164:167], v[172:175], v[58:61]
	v_mfma_f32_16x16x32_bf16 v[54:57], v[156:159], v[192:195], v[54:57]
	v_mfma_f32_16x16x32_bf16 v[50:53], v[164:167], v[192:195], v[50:53]
	v_mfma_f32_16x16x32_bf16 v[38:41], v[156:159], v[200:203], v[38:41]
	v_mfma_f32_16x16x32_bf16 v[34:37], v[164:167], v[200:203], v[34:37]
	v_mfma_f32_16x16x32_bf16 v[22:25], v[156:159], v[208:211], v[22:25]
	v_mfma_f32_16x16x32_bf16 v[18:21], v[164:167], v[208:211], v[18:21]
	v_mfma_f32_16x16x32_bf16 v[62:65], v[160:163], v[188:191], v[62:65]
	v_mfma_f32_16x16x32_bf16 v[58:61], v[168:171], v[188:191], v[58:61]
	v_mfma_f32_16x16x32_bf16 v[54:57], v[160:163], v[196:199], v[54:57]
	v_mfma_f32_16x16x32_bf16 v[50:53], v[168:171], v[196:199], v[50:53]
	v_mfma_f32_16x16x32_bf16 v[38:41], v[160:163], v[204:207], v[38:41]
	v_mfma_f32_16x16x32_bf16 v[34:37], v[168:171], v[204:207], v[34:37]
	v_mfma_f32_16x16x32_bf16 v[22:25], v[160:163], v[212:215], v[22:25]
	v_mfma_f32_16x16x32_bf16 v[18:21], v[168:171], v[212:215], v[18:21]
	s_setprio 0
	s_barrier
	s_add_u32 s20, s66, 0xb0000
	s_addc_u32 s21, s67, 0
	s_add_i32 s19, s22, s9
	v_lshl_add_u64 v[156:157], s[20:21], 0, v[144:145]
	s_mov_b32 m0, s19
	s_nop 0
	global_load_lds_dwordx4 v[156:157], off
	v_lshl_add_u64 v[156:157], s[20:21], 0, v[140:141]
	s_add_i32 m0, s19, 0x2000
	s_nop 0
	global_load_lds_dwordx4 v[156:157], off
	s_cmp_eq_u32 s98, 0
	s_cbranch_scc1 .Lgdr818_n
	s_waitcnt vmcnt(24)
	s_mov_b32 s98, 0
	s_branch .Lgdr818_j
